# grid barriers: leaders no longer bump the now unread TOPGEN / per-XCD release counters nor wait for those atomics
# baseline (speedup 1.0000x reference)
; __device__ __forceinline__ unsigned xb_ld(unsigned* p)              { return __hip_atomic_load(p, __ATOMIC_RELAXED, __HIP_MEMORY_SCOPE_AGENT); }
; __device__ __forceinline__ unsigned xb_add(unsigned* p, unsigned v) { return __hip_atomic_fetch_add(p, v, __ATOMIC_RELAXED, __HIP_MEMORY_SCOPE_AGENT); }
; #define XB_SPIN(cond, bar) do { unsigned _sp = 0; while (cond) { __builtin_amdgcn_s_sleep(1); \
;     if ((++_sp & 255u) == 0u) { if (xb_ld(&(bar)[XB_TMO])) break; if (_sp > XB_SPIN_CAP) { atomicAdd(&(bar)[XB_TMO], 1u); break; } } } } while (0)
; __device__ __forceinline__ void xcd_barrier(const XcdBarrier& b) {
;     ...
;             const unsigned og = xb_add(&bar[XB_TOP], 1u);
;             const unsigned tg = og / nx;
;             if (og + 1u == (tg + 1u) * nx) xb_add(&bar[XB_TOPGEN], 1u);
;             else XB_SPIN(xb_ld(&bar[XB_TOPGEN]) == tg, bar);
.LBB0_166:
	s_or_b64 exec, exec, s[10:11]
	v_cvt_f32_u32_e32 v3, v0
	s_waitcnt vmcnt(0)
	v_readfirstlane_b32 s8, v2
	s_add_u32 s10, s70, 0x2303500
	s_addc_u32 s11, s71, 0
	v_rcp_iflag_f32_e32 v3, v3
	v_add_u32_e32 v1, s8, v1
	v_add_u32_e32 v4, 1, v1
	s_mov_b64 s[12:13], 0
	v_mul_f32_e32 v2, 0x4f7ffffe, v3
	v_cvt_u32_f32_e32 v2, v2
	v_sub_u32_e32 v3, 0, v0
	v_mul_lo_u32 v3, v3, v2
	v_mul_hi_u32 v3, v2, v3
	v_add_u32_e32 v2, v2, v3
	v_mul_hi_u32 v2, v1, v2
	v_mul_lo_u32 v3, v2, v0
	v_sub_u32_e32 v1, v1, v3
	v_add_u32_e32 v5, 1, v2
	v_cmp_ge_u32_e32 vcc, v1, v0
	v_sub_u32_e32 v3, v1, v0
	s_nop 0
	v_cndmask_b32_e32 v2, v2, v5, vcc
	v_cndmask_b32_e32 v1, v1, v3, vcc
	v_add_u32_e32 v3, 1, v2
	v_cmp_ge_u32_e32 vcc, v1, v0
	s_nop 1
	v_cndmask_b32_e32 v2, v2, v3, vcc
	v_mul_lo_u32 v1, v0, v2
	v_add_u32_e32 v0, v1, v0
	v_cmp_ne_u32_e32 vcc, v4, v0
	v_mov_b32_e32 v3, v0
	v_mov_b32_e32 v5, 0x2303000
	v_mov_b64_e32 v[0:1], s[10:11]
	s_and_saveexec_b64 s[8:9], vcc
	s_cbranch_execz .LBB0_178
	v_mov_b32_e32 v0, 0
	global_load_dword v1, v5, s[70:71] offset:1024 sc1
	s_mov_b64 s[20:21], 0
	s_waitcnt vmcnt(0)
	v_cmp_lt_u32_e32 vcc, v1, v3
	s_and_saveexec_b64 s[18:19], vcc
	s_cbranch_execz .LBB0_177
	s_add_u32 s12, s70, 0x2300200
	s_addc_u32 s13, s71, 0
	s_mov_b32 s14, 1
	s_branch .LBB0_170

; __device__ __forceinline__ unsigned xb_add(unsigned* p, unsigned v) { return __hip_atomic_fetch_add(p, v, __ATOMIC_RELAXED, __HIP_MEMORY_SCOPE_AGENT); }
; __device__ __forceinline__ void xcd_barrier(const XcdBarrier& b) {
;     ...
;             xb_add(&bar[XB_XGEN(b.x)], 1u);
;             asm volatile("s_waitcnt vmcnt(0)" ::: "memory");
.LBB0_180:
	s_or_b64 exec, exec, s[8:9]
	s_mov_b64 s[8:9], exec
	v_mbcnt_lo_u32_b32 v0, s8, 0
	v_mbcnt_hi_u32_b32 v0, s9, v0
	v_cmp_eq_u32_e32 vcc, 0, v0
	s_waitcnt vmcnt(0)
	s_and_saveexec_b64 s[10:11], vcc
	s_cbranch_execz .LBB0_182
	s_bcnt1_i32_b64 s8, s[8:9]
	v_mov_b32_e32 v0, 0x2000
	v_mov_b32_e32 v1, s8
.LBB0_182:
	s_or_b64 exec, exec, s[10:11]
	s_waitcnt vmcnt(0)

; __device__ __forceinline__ unsigned xb_ld(unsigned* p)              { return __hip_atomic_load(p, __ATOMIC_RELAXED, __HIP_MEMORY_SCOPE_AGENT); }
; __device__ __forceinline__ unsigned xb_add(unsigned* p, unsigned v) { return __hip_atomic_fetch_add(p, v, __ATOMIC_RELAXED, __HIP_MEMORY_SCOPE_AGENT); }
; #define XB_SPIN(cond, bar) do { unsigned _sp = 0; while (cond) { __builtin_amdgcn_s_sleep(1); \
;     if ((++_sp & 255u) == 0u) { if (xb_ld(&(bar)[XB_TMO])) break; if (_sp > XB_SPIN_CAP) { atomicAdd(&(bar)[XB_TMO], 1u); break; } } } } while (0)
; __device__ __forceinline__ void xcd_barrier(const XcdBarrier& b) {
;     ...
;             const unsigned og = xb_add(&bar[XB_TOP], 1u);
;             const unsigned tg = og / nx;
;             if (og + 1u == (tg + 1u) * nx) xb_add(&bar[XB_TOPGEN], 1u);
;             else XB_SPIN(xb_ld(&bar[XB_TOPGEN]) == tg, bar);
.LBB0_259:
	s_or_b64 exec, exec, s[8:9]
	v_cvt_f32_u32_e32 v3, v0
	s_waitcnt vmcnt(0)
	v_readfirstlane_b32 s6, v2
	s_add_u32 s8, s70, 0x2303500
	s_addc_u32 s9, s71, 0
	v_rcp_iflag_f32_e32 v3, v3
	v_add_u32_e32 v1, s6, v1
	v_add_u32_e32 v4, 1, v1
	s_mov_b64 s[10:11], 0
	v_mul_f32_e32 v2, 0x4f7ffffe, v3
	v_cvt_u32_f32_e32 v2, v2
	v_sub_u32_e32 v3, 0, v0
	v_mul_lo_u32 v3, v3, v2
	v_mul_hi_u32 v3, v2, v3
	v_add_u32_e32 v2, v2, v3
	v_mul_hi_u32 v2, v1, v2
	v_mul_lo_u32 v3, v2, v0
	v_sub_u32_e32 v1, v1, v3
	v_add_u32_e32 v5, 1, v2
	v_cmp_ge_u32_e32 vcc, v1, v0
	v_sub_u32_e32 v3, v1, v0
	s_nop 0
	v_cndmask_b32_e32 v2, v2, v5, vcc
	v_cndmask_b32_e32 v1, v1, v3, vcc
	v_add_u32_e32 v3, 1, v2
	v_cmp_ge_u32_e32 vcc, v1, v0
	s_nop 1
	v_cndmask_b32_e32 v2, v2, v3, vcc
	v_mul_lo_u32 v1, v0, v2
	v_add_u32_e32 v0, v1, v0
	v_cmp_ne_u32_e32 vcc, v4, v0
	v_mov_b32_e32 v3, v0
	v_mov_b32_e32 v5, 0x2303000
	v_mov_b64_e32 v[0:1], s[8:9]
	s_and_saveexec_b64 s[6:7], vcc
	s_cbranch_execz .LBB0_271
	v_mov_b32_e32 v0, 0
	global_load_dword v1, v5, s[70:71] offset:1024 sc1
	s_mov_b64 s[18:19], 0
	s_waitcnt vmcnt(0)
	v_cmp_lt_u32_e32 vcc, v1, v3
	s_and_saveexec_b64 s[12:13], vcc
	s_cbranch_execz .LBB0_270
	s_add_u32 s10, s70, 0x2300200
	s_addc_u32 s11, s71, 0
	s_mov_b32 s14, 1
	s_branch .LBB0_263

; __device__ __forceinline__ unsigned xb_add(unsigned* p, unsigned v) { return __hip_atomic_fetch_add(p, v, __ATOMIC_RELAXED, __HIP_MEMORY_SCOPE_AGENT); }
; __device__ __forceinline__ void xcd_barrier(const XcdBarrier& b) {
;     ...
;             xb_add(&bar[XB_XGEN(b.x)], 1u);
;             asm volatile("s_waitcnt vmcnt(0)" ::: "memory");
.LBB0_273:
	s_or_b64 exec, exec, s[6:7]
	s_mov_b64 s[6:7], exec
	v_mbcnt_lo_u32_b32 v0, s6, 0
	v_mbcnt_hi_u32_b32 v0, s7, v0
	v_cmp_eq_u32_e32 vcc, 0, v0
	s_waitcnt vmcnt(0)
	s_and_saveexec_b64 s[8:9], vcc
	s_cbranch_execz .LBB0_275
	s_bcnt1_i32_b64 s6, s[6:7]
	v_mov_b32_e32 v0, 0x2000
	v_mov_b32_e32 v1, s6
.LBB0_275:
	s_or_b64 exec, exec, s[8:9]
	s_waitcnt vmcnt(0)

; __device__ __forceinline__ unsigned xb_add(unsigned* p, unsigned v) { return __hip_atomic_fetch_add(p, v, __ATOMIC_RELAXED, __HIP_MEMORY_SCOPE_AGENT); }
; __device__ __forceinline__ void xcd_barrier(const XcdBarrier& b) {
;     ...
;             xb_add(&bar[XB_XGEN(b.x)], 1u);
;             asm volatile("s_waitcnt vmcnt(0)" ::: "memory");
.LBB0_340:
	s_or_b64 exec, exec, s[8:9]
	s_mov_b64 s[8:9], exec
	v_mbcnt_lo_u32_b32 v0, s8, 0
	v_mbcnt_hi_u32_b32 v0, s9, v0
	v_cmp_eq_u32_e32 vcc, 0, v0
	s_waitcnt vmcnt(0)
	s_and_saveexec_b64 s[10:11], vcc
	s_cbranch_execz .LBB0_342
	s_bcnt1_i32_b64 s8, s[8:9]
	v_mov_b32_e32 v0, 0x2000
	v_mov_b32_e32 v1, s8
.LBB0_342:
	s_or_b64 exec, exec, s[10:11]
	s_waitcnt vmcnt(0)

; __device__ __forceinline__ unsigned xb_add(unsigned* p, unsigned v) { return __hip_atomic_fetch_add(p, v, __ATOMIC_RELAXED, __HIP_MEMORY_SCOPE_AGENT); }
; __device__ __forceinline__ void xcd_barrier(const XcdBarrier& b) {
;     ...
;             xb_add(&bar[XB_XGEN(b.x)], 1u);
;             asm volatile("s_waitcnt vmcnt(0)" ::: "memory");
.LBB0_411:
	s_or_b64 exec, exec, s[8:9]
	s_mov_b64 s[8:9], exec
	v_mbcnt_lo_u32_b32 v0, s8, 0
	v_mbcnt_hi_u32_b32 v0, s9, v0
	v_cmp_eq_u32_e32 vcc, 0, v0
	s_waitcnt vmcnt(0)
	s_and_saveexec_b64 s[10:11], vcc
	s_cbranch_execz .LBB0_413
	s_bcnt1_i32_b64 s8, s[8:9]
	v_mov_b32_e32 v0, 0x2000
	v_mov_b32_e32 v1, s8
.LBB0_413:
	s_or_b64 exec, exec, s[10:11]
	s_waitcnt vmcnt(0)

; __device__ __forceinline__ unsigned xb_add(unsigned* p, unsigned v) { return __hip_atomic_fetch_add(p, v, __ATOMIC_RELAXED, __HIP_MEMORY_SCOPE_AGENT); }
; __device__ __forceinline__ void xcd_barrier(const XcdBarrier& b) {
;     ...
;             xb_add(&bar[XB_XGEN(b.x)], 1u);
;             asm volatile("s_waitcnt vmcnt(0)" ::: "memory");
.LBB0_470:
	s_or_b64 exec, exec, s[8:9]
	s_mov_b64 s[8:9], exec
	v_mbcnt_lo_u32_b32 v0, s8, 0
	v_mbcnt_hi_u32_b32 v0, s9, v0
	v_cmp_eq_u32_e32 vcc, 0, v0
	s_waitcnt vmcnt(0)
	s_and_saveexec_b64 s[10:11], vcc
	s_cbranch_execz .LBB0_472
	s_bcnt1_i32_b64 s8, s[8:9]
	v_mov_b32_e32 v0, 0x2000
	v_mov_b32_e32 v1, s8
.LBB0_472:
	s_or_b64 exec, exec, s[10:11]
	s_waitcnt vmcnt(0)

; __device__ __forceinline__ unsigned xb_add(unsigned* p, unsigned v) { return __hip_atomic_fetch_add(p, v, __ATOMIC_RELAXED, __HIP_MEMORY_SCOPE_AGENT); }
; __device__ __forceinline__ void xcd_barrier(const XcdBarrier& b) {
;     ...
;             xb_add(&bar[XB_XGEN(b.x)], 1u);
;             asm volatile("s_waitcnt vmcnt(0)" ::: "memory");
.LBB0_571:
	s_or_b64 exec, exec, s[8:9]
	s_mov_b64 s[8:9], exec
	v_mbcnt_lo_u32_b32 v0, s8, 0
	v_mbcnt_hi_u32_b32 v0, s9, v0
	v_cmp_eq_u32_e32 vcc, 0, v0
	s_waitcnt vmcnt(0)
	s_and_saveexec_b64 s[10:11], vcc
	s_cbranch_execz .LBB0_573
	s_bcnt1_i32_b64 s8, s[8:9]
	v_mov_b32_e32 v0, 0x2000
	v_mov_b32_e32 v1, s8
.LBB0_573:
	s_or_b64 exec, exec, s[10:11]
	s_waitcnt vmcnt(0)

; __device__ __forceinline__ unsigned xb_add(unsigned* p, unsigned v) { return __hip_atomic_fetch_add(p, v, __ATOMIC_RELAXED, __HIP_MEMORY_SCOPE_AGENT); }
; __device__ __forceinline__ void xcd_barrier(const XcdBarrier& b) {
;     ...
;             xb_add(&bar[XB_XGEN(b.x)], 1u);
;             asm volatile("s_waitcnt vmcnt(0)" ::: "memory");
.LBB0_672:
	s_or_b64 exec, exec, s[8:9]
	s_mov_b64 s[8:9], exec
	v_mbcnt_lo_u32_b32 v0, s8, 0
	v_mbcnt_hi_u32_b32 v0, s9, v0
	v_cmp_eq_u32_e32 vcc, 0, v0
	s_waitcnt vmcnt(0)
	s_and_saveexec_b64 s[10:11], vcc
	s_cbranch_execz .LBB0_674
	s_bcnt1_i32_b64 s8, s[8:9]
	v_mov_b32_e32 v0, 0x2000
	v_mov_b32_e32 v1, s8
.LBB0_674:
	s_or_b64 exec, exec, s[10:11]
	s_waitcnt vmcnt(0)

; __device__ __forceinline__ unsigned xb_add(unsigned* p, unsigned v) { return __hip_atomic_fetch_add(p, v, __ATOMIC_RELAXED, __HIP_MEMORY_SCOPE_AGENT); }
; __device__ __forceinline__ void xcd_barrier(const XcdBarrier& b) {
;     ...
;             xb_add(&bar[XB_XGEN(b.x)], 1u);
;             asm volatile("s_waitcnt vmcnt(0)" ::: "memory");
.LBB0_741:
	s_or_b64 exec, exec, s[8:9]
	s_mov_b64 s[8:9], exec
	v_mbcnt_lo_u32_b32 v0, s8, 0
	v_mbcnt_hi_u32_b32 v0, s9, v0
	v_cmp_eq_u32_e32 vcc, 0, v0
	s_waitcnt vmcnt(0)
	s_and_saveexec_b64 s[10:11], vcc
	s_cbranch_execz .LBB0_743
	s_bcnt1_i32_b64 s8, s[8:9]
	v_mov_b32_e32 v0, 0x2000
	v_mov_b32_e32 v1, s8
.LBB0_743:
	s_or_b64 exec, exec, s[10:11]
	s_waitcnt vmcnt(0)

; __device__ __forceinline__ unsigned xb_ld(unsigned* p)              { return __hip_atomic_load(p, __ATOMIC_RELAXED, __HIP_MEMORY_SCOPE_AGENT); }
; __device__ __forceinline__ unsigned xb_add(unsigned* p, unsigned v) { return __hip_atomic_fetch_add(p, v, __ATOMIC_RELAXED, __HIP_MEMORY_SCOPE_AGENT); }
; #define XB_SPIN(cond, bar) do { unsigned _sp = 0; while (cond) { __builtin_amdgcn_s_sleep(1); \
;     if ((++_sp & 255u) == 0u) { if (xb_ld(&(bar)[XB_TMO])) break; if (_sp > XB_SPIN_CAP) { atomicAdd(&(bar)[XB_TMO], 1u); break; } } } } while (0)
; __device__ __forceinline__ void xcd_barrier(const XcdBarrier& b) {
;     ...
;             const unsigned og = xb_add(&bar[XB_TOP], 1u);
;             const unsigned tg = og / nx;
;             if (og + 1u == (tg + 1u) * nx) xb_add(&bar[XB_TOPGEN], 1u);
;             else XB_SPIN(xb_ld(&bar[XB_TOPGEN]) == tg, bar);
.LBB0_802:
	s_or_b64 exec, exec, s[10:11]
	v_cvt_f32_u32_e32 v3, v0
	s_waitcnt vmcnt(0)
	v_readfirstlane_b32 s3, v2
	s_add_u32 s10, s70, 0x2303500
	s_addc_u32 s11, s71, 0
	v_rcp_iflag_f32_e32 v3, v3
	v_add_u32_e32 v1, s3, v1
	v_add_u32_e32 v4, 1, v1
	s_mov_b64 s[12:13], 0
	v_mul_f32_e32 v2, 0x4f7ffffe, v3
	v_cvt_u32_f32_e32 v2, v2
	v_sub_u32_e32 v3, 0, v0
	v_mul_lo_u32 v3, v3, v2
	v_mul_hi_u32 v3, v2, v3
	v_add_u32_e32 v2, v2, v3
	v_mul_hi_u32 v2, v1, v2
	v_mul_lo_u32 v3, v2, v0
	v_sub_u32_e32 v1, v1, v3
	v_add_u32_e32 v5, 1, v2
	v_cmp_ge_u32_e32 vcc, v1, v0
	v_sub_u32_e32 v3, v1, v0
	s_nop 0
	v_cndmask_b32_e32 v2, v2, v5, vcc
	v_cndmask_b32_e32 v1, v1, v3, vcc
	v_add_u32_e32 v3, 1, v2
	v_cmp_ge_u32_e32 vcc, v1, v0
	s_nop 1
	v_cndmask_b32_e32 v2, v2, v3, vcc
	v_mul_lo_u32 v1, v0, v2
	v_add_u32_e32 v0, v1, v0
	v_cmp_ne_u32_e32 vcc, v4, v0
	v_mov_b32_e32 v3, v0
	v_mov_b32_e32 v5, 0x2303000
	v_mov_b64_e32 v[0:1], s[10:11]
	s_and_saveexec_b64 s[8:9], vcc
	s_cbranch_execz .LBB0_814
	v_mov_b32_e32 v0, 0
	global_load_dword v1, v5, s[70:71] offset:1024 sc1
	s_mov_b64 s[18:19], 0
	s_waitcnt vmcnt(0)
	v_cmp_lt_u32_e32 vcc, v1, v3
	s_and_saveexec_b64 s[14:15], vcc
	s_cbranch_execz .LBB0_813
	s_add_u32 s12, s70, 0x2300200
	s_addc_u32 s13, s71, 0
	s_mov_b32 s3, 1
	s_branch .LBB0_806

; __device__ __forceinline__ unsigned xb_add(unsigned* p, unsigned v) { return __hip_atomic_fetch_add(p, v, __ATOMIC_RELAXED, __HIP_MEMORY_SCOPE_AGENT); }
; __device__ __forceinline__ void xcd_barrier(const XcdBarrier& b) {
;     ...
;             xb_add(&bar[XB_XGEN(b.x)], 1u);
;             asm volatile("s_waitcnt vmcnt(0)" ::: "memory");
.LBB0_816:
	s_or_b64 exec, exec, s[8:9]
	s_mov_b64 s[8:9], exec
	v_mbcnt_lo_u32_b32 v0, s8, 0
	v_mbcnt_hi_u32_b32 v0, s9, v0
	v_cmp_eq_u32_e32 vcc, 0, v0
	s_waitcnt vmcnt(0)
	s_and_saveexec_b64 s[10:11], vcc
	s_cbranch_execz .LBB0_818
	s_bcnt1_i32_b64 s3, s[8:9]
	v_mov_b32_e32 v0, 0x2000
	v_mov_b32_e32 v1, s3
.LBB0_818:
	s_or_b64 exec, exec, s[10:11]
	s_waitcnt vmcnt(0)
